# retention: wc=0 waves run the deferred weight-conversion store before the partner-P MFMAs, wc=1 after (stagger per SIMD)
# speedup vs baseline: 1.0006x; 1.0006x over previous
; __device__ __forceinline__ CvU cv_decode(ArgsP a, unsigned char* ws, int hi, int layer) {
;     CvU u; int fi = hi >> 1; const int half = hi & 1; int l = layer, kind;
;     if (fi < CV_GLU) kind = 0; else if ((fi -= CV_GLU) < CV_OUT) kind = 1; else { fi -= CV_OUT; kind = 2; l = layer + 1; }
;     int kb, nb;
; __device__ __forceinline__ void p2_ret(const Frame& F, ArgsP a, int layer) {
;     ...
;                 if (cv) { const CvU cu = cv_decode(a, F.ws, cvhi, layer); cv_store(cu, lane, cvv, cvsc); cvhi += cvs; }
.Lrk_skip:
	s_mov_b32 s84, 0
	s_cmp_lg_u32 s80, 0
	s_cbranch_scc1 .Lca_skip
	s_and_b64 vcc, exec, s[38:39]
	s_cbranch_vccnz .Lca_skip
	v_mov_b32_e32 v227, v207
	s_ashr_i32 s14, s36, 1
	s_cmpk_lt_i32 s14, 0x400
	s_cselect_b64 s[4:5], -1, 0
	s_mov_b64 s[70:71], 0
	s_and_b64 vcc, exec, s[4:5]
	s_cbranch_vccnz .Lca_394
	s_mov_b64 s[46:47], -1
	s_cmpk_gt_u32 s14, 0x13ff
	s_mov_b64 s[6:7], -1
	s_cbranch_scc0 .Lca_391
	s_add_i32 s12, s14, 0xffffec00
	s_mov_b64 s[6:7], 0

; __device__ __forceinline__ CvU cv_decode(ArgsP a, unsigned char* ws, int hi, int layer) {
;     ...
;     int kb, nb;
;     if (kind == 0) { u.W = a->in[I_WGLU] + (size_t)l * DS * DS; u.WT = (bf16_t*)(ws + WS_WTGLU + (size_t)l * DS * DS); u.K = DS; u.N = DS; kb = fi / (DS / 64); nb = fi % (DS / 64); }
;     else if (kind == 1) { u.W = a->in[I_WOUT] + (size_t)l * DM * DM; u.WT = (bf16_t*)(ws + WS_WTOUT) + (size_t)l * DM * DM; u.K = DM; u.N = DM; kb = fi / (DM / 64); nb = fi % (DM / 64); }
;     else { u.W = a->in[I_WIN] + (size_t)l * DM * NPROJ; u.WT = (bf16_t*)(ws + WS_WTIN) + (size_t)l * NPROJ * DM; u.K = DM; u.N = NPROJ; kb = fi / (NPROJ / 64); nb = fi % (NPROJ / 64); }
;     u.k0 = 64 * kb + 32 * half; u.n0 = 64 * nb; u.n0d = u.n0; u.rowperm = 0;
;     u.ks = nullptr; u.f8 = (kind == 0);
.Lca_395:
	v_cndmask_b32_e64 v198, 0, 1, s[4:5]
	v_cmp_ne_u32_e64 s[38:39], 1, v198
	s_andn2_b64 vcc, exec, s[4:5]
	s_mov_b64 s[12:13], -1
	s_cbranch_vccnz .Lca_399
	s_lshl_b64 s[4:5], s[6:7], 22
	s_add_u32 s4, s9, s4
	s_addc_u32 s5, s58, s5
	s_ashr_i32 s12, s14, 31
	s_lshr_b32 s12, s12, 27
	s_add_i32 s12, s14, s12
	s_ashr_i32 s15, s12, 5
	s_andn2_b32 s12, s12, 31
	s_sub_i32 s76, s14, s12
	s_mov_b64 s[12:13], 0x800
	s_cbranch_execz .Lca_400

; __device__ __forceinline__ void cv_load(const CvU& u, int lane, f32x4 (&v)[8], f32x4 (&sc)[2]) {
;     const int nq = lane & 15, kq = lane >> 4;
;     const float* wp = u.W + (size_t)(u.k0 + 8 * kq) * u.N + u.n0 + 4 * nq;
; #pragma unroll
;     for (int i = 0; i < 8; ++i) v[i] = __builtin_nontemporal_load((const f32x4*)(wp + (size_t)i * u.N));
;     if (u.ks) { sc[0] = *(const f32x4*)(u.ks + 8 * kq); sc[1] = *(const f32x4*)(u.ks + 8 * kq + 4); }
;     else { sc[0] = (f32x4){1.f, 1.f, 1.f, 1.f}; sc[1] = sc[0]; }
; }
; __device__ __forceinline__ void cv_store(const CvU& u, int lane, const f32x4 (&v)[8], const f32x4 (&sc)[2]) {
;     const int nq = lane & 15, kq = lane >> 4;
;     if (u.f8) {
; #pragma unroll
;         for (int c = 0; c < 4; ++c) { unsigned char* dst = (unsigned char*)u.WT + (size_t)(u.n0d + 4 * nq + c) * u.K + u.k0 + 8 * kq;
;             u32x2 o; o.x = pk4_fp8(v[0][c] * F8_SW, v[1][c] * F8_SW, v[2][c] * F8_SW, v[3][c] * F8_SW); o.y = pk4_fp8(v[4][c] * F8_SW, v[5][c] * F8_SW, v[6][c] * F8_SW, v[7][c] * F8_SW);
;             *(u32x2*)dst = o; }
.Lca_406:
	s_add_i32 s85, s30, 0x80
	s_cmp_eq_u32 s85, s11
	s_cbranch_scc1 .Lca_w4
	s_waitcnt vmcnt(8)
	s_branch .Lca_wd
.Lca_w4:
	s_waitcnt vmcnt(4)
.Lca_wd:
	s_lshl_b32 s14, s15, 6
	s_lshl_b32 s15, s36, 5
	v_and_b32_e32 v200, 15, v227
	v_ashrrev_i32_e32 v227, 4, v227
	s_and_b32 s15, s15, 32
	v_lshlrev_b32_e32 v198, 3, v227
	s_or_b32 s70, s14, s15
	s_and_b64 vcc, exec, s[38:39]
	v_ashrrev_i32_e32 v199, 31, v198
	s_cbranch_vccnz .Lca_408
	v_mul_f32_e32 v201, 0x42800000, v2
	v_mul_f32_e32 v213, 0x42800000, v6
	v_mov_b32_e32 v212, v1
	v_cvt_pk_fp8_f32 v212, v201, v213
	v_mul_f32_e32 v214, 0x42800000, v10
	v_mul_f32_e32 v215, 0x42800000, v14
	v_mul_f32_e32 v201, 0x42800000, v18
	v_cvt_pk_fp8_f32 v212, v214, v215 op_sel:[0,0,1]
	v_mul_f32_e32 v214, 0x42800000, v22
	v_mov_b32_e32 v213, v1
	v_cvt_pk_fp8_f32 v213, v201, v214
	v_mul_f32_e32 v215, 0x42800000, v26
	v_mul_f32_e32 v216, 0x42800000, v30
	v_lshl_add_u32 v227, v200, 2, s13
	v_mov_b64_e32 v[202:203], s[4:5]
	v_cvt_pk_fp8_f32 v213, v215, v216 op_sel:[0,0,1]
	v_mad_i64_i32 v[204:205], s[6:7], s12, v227, v[202:203]
	s_ashr_i32 s71, s70, 31
	v_lshl_add_u64 v[204:205], v[204:205], 0, s[70:71]
	v_lshl_add_u64 v[204:205], v[204:205], 0, v[198:199]
	v_add_u32_e32 v201, 1, v227
	global_store_dwordx2 v[204:205], v[212:213], off
	v_mad_i64_i32 v[204:205], s[6:7], s12, v201, v[202:203]
	v_mul_f32_e32 v201, 0x42800000, v3
	v_mul_f32_e32 v213, 0x42800000, v7
	v_mov_b32_e32 v212, v1
	v_cvt_pk_fp8_f32 v212, v201, v213
	v_mul_f32_e32 v214, 0x42800000, v11
	v_mul_f32_e32 v215, 0x42800000, v15
	v_mul_f32_e32 v201, 0x42800000, v19
	v_cvt_pk_fp8_f32 v212, v214, v215 op_sel:[0,0,1]
	v_mul_f32_e32 v214, 0x42800000, v23
	v_mov_b32_e32 v213, v1
	v_cvt_pk_fp8_f32 v213, v201, v214
	v_mul_f32_e32 v215, 0x42800000, v27
	v_mul_f32_e32 v216, 0x42800000, v31
	v_lshl_add_u64 v[204:205], v[204:205], 0, s[70:71]
	v_cvt_pk_fp8_f32 v213, v215, v216 op_sel:[0,0,1]
	v_lshl_add_u64 v[204:205], v[204:205], 0, v[198:199]
	v_add_u32_e32 v201, 2, v227
	v_mul_f32_e32 v214, 0x42800000, v12
	global_store_dwordx2 v[204:205], v[212:213], off
	v_mad_i64_i32 v[204:205], s[6:7], s12, v201, v[202:203]
	v_mul_f32_e32 v201, 0x42800000, v4
	v_mul_f32_e32 v213, 0x42800000, v8
	v_mov_b32_e32 v212, v1
	v_cvt_pk_fp8_f32 v212, v201, v213
	v_mul_f32_e32 v215, 0x42800000, v16
	v_mul_f32_e32 v201, 0x42800000, v20
	v_mov_b32_e32 v213, v1
	v_cvt_pk_fp8_f32 v212, v214, v215 op_sel:[0,0,1]
	v_mul_f32_e32 v214, 0x42800000, v24
	v_cvt_pk_fp8_f32 v213, v201, v214
	v_mul_f32_e32 v215, 0x42800000, v28
	v_mul_f32_e32 v216, 0x42800000, v32
	v_lshl_add_u64 v[204:205], v[204:205], 0, s[70:71]
	v_cvt_pk_fp8_f32 v213, v215, v216 op_sel:[0,0,1]
	v_lshl_add_u64 v[204:205], v[204:205], 0, v[198:199]
	v_add_u32_e32 v227, 3, v227
	v_mad_i64_i32 v[202:203], s[6:7], s12, v227, v[202:203]
	global_store_dwordx2 v[204:205], v[212:213], off
	v_mul_f32_e32 v227, 0x42800000, v5
	v_mul_f32_e32 v201, 0x42800000, v9
	v_mov_b32_e32 v204, v1
	v_cvt_pk_fp8_f32 v204, v227, v201
	v_mul_f32_e32 v205, 0x42800000, v13
	v_mul_f32_e32 v212, 0x42800000, v17
	v_mul_f32_e32 v227, 0x42800000, v21
	v_cvt_pk_fp8_f32 v204, v205, v212 op_sel:[0,0,1]
	v_mul_f32_e32 v201, 0x42800000, v25
	v_mov_b32_e32 v205, v1
	v_cvt_pk_fp8_f32 v205, v227, v201
	v_mul_f32_e32 v212, 0x42800000, v29
	v_mul_f32_e32 v213, 0x42800000, v33
	v_lshl_add_u64 v[202:203], v[202:203], 0, s[70:71]
	v_cvt_pk_fp8_f32 v205, v212, v213 op_sel:[0,0,1]
	v_lshl_add_u64 v[202:203], v[202:203], 0, v[198:199]
	s_mov_b64 s[6:7], 0
	global_store_dwordx2 v[202:203], v[204:205], off
; __device__ __forceinline__ unsigned cvt_pk_bf16(float lo, float hi) { unsigned r; asm volatile("v_cvt_pk_bf16_f32 %0, %1, %2" : "=v"(r) : "v"(lo), "v"(hi)); return r; }
; #define RT_VRD(dst, g) do { _Pragma("unroll") for (int j_ = 0; j_ < 2; ++j_) { const int jj_ = 2 * ((g) & 1) + j_; dst[j_] = *(const LAS bf16x8*)(vb + ((g) >> 1) * 4096 + (((4 * (jj_ >> 1) + 2 * (jj_ & 1) + hh) << 4) ^ m4)); } } while (0)
; #define RT_VMM(src, g) do { _Pragma("unroll") for (int j_ = 0; j_ < 2; ++j_) { const int jj_ = 2 * ((g) & 1) + j_; oacc[(g) >> 1] = __builtin_amdgcn_mfma_f32_32x32x16_bf16(src[j_], pf[jj_ >> 1][jj_ & 1], oacc[(g) >> 1], 0, 0, 0); } } while (0)
; __device__ __forceinline__ void cv_store(const CvU& u, int lane, const f32x4 (&v)[8], const f32x4 (&sc)[2]) {
;     ...
; #pragma unroll
;     for (int c = 0; c < 4; ++c) { bf16_t* dst = u.WT + (size_t)(u.rowperm ? u.n0d + 64 * (nq >> 3) + ((4 * nq + c) & 31) : u.n0d + 4 * nq + c) * u.K + u.k0 + 8 * kq;
;         u32x4 o;
;         o.x = cvt_pk_bf16(v[0][c] * sc[0][0], v[1][c] * sc[0][1]); o.y = cvt_pk_bf16(v[2][c] * sc[0][2], v[3][c] * sc[0][3]);
;         o.z = cvt_pk_bf16(v[4][c] * sc[1][0], v[5][c] * sc[1][1]); o.w = cvt_pk_bf16(v[6][c] * sc[1][2], v[7][c] * sc[1][3]);
;         *(u32x4*)dst = o; }
; __device__ __forceinline__ void p2_ret(const Frame& F, ArgsP a, int layer) {
;     ...
;                   bf16x8 va[2], vc[2];
;                   RT_VRD(va, 0); __builtin_amdgcn_sched_barrier(0);
;                   RT_VRD(vc, 1); RT_VMM(va, 0); __builtin_amdgcn_sched_barrier(0);
;                   RT_VRD(va, 2); RT_VMM(vc, 1); __builtin_amdgcn_sched_barrier(0);
;                   RT_VRD(vc, 3); RT_VMM(va, 2); __builtin_amdgcn_sched_barrier(0);
;                   RT_VRD(va, 4); RT_VMM(vc, 3); __builtin_amdgcn_sched_barrier(0);
;                   RT_VRD(vc, 5); RT_VMM(va, 4); __builtin_amdgcn_sched_barrier(0);
;                   RT_VRD(va, 6); RT_VMM(vc, 5); __builtin_amdgcn_sched_barrier(0);
;                   RT_VRD(vc, 7); RT_VMM(va, 6); __builtin_amdgcn_sched_barrier(0);
;                   RT_VMM(vc, 7); __builtin_amdgcn_sched_barrier(0);
;     ...
;                 }
;                 asm volatile("s_waitcnt vmcnt(0)" ::: "memory");
.Lca_408:
	s_andn2_b64 vcc, exec, s[6:7]
	s_cbranch_vccnz .Lca_done
	v_lshlrev_b32_e32 v227, 3, v200
	v_lshlrev_b32_e32 v200, 2, v200
	v_and_b32_e32 v201, 28, v200
	v_and_or_b32 v227, v227, 64, v201
	v_cndmask_b32_e64 v227, v227, v200, s[46:47]
	v_add_u32_e32 v227, s13, v227
	v_mad_i64_i32 v[200:201], s[6:7], s12, v227, 0
	s_ashr_i32 s71, s70, 31
	v_lshl_add_u64 v[200:201], v[200:201], 1, s[4:5]
	s_lshl_b64 s[6:7], s[70:71], 1
	v_lshl_add_u64 v[200:201], v[200:201], 0, s[6:7]
	v_lshlrev_b64 v[202:203], 1, v[198:199]
	v_mul_f32_e32 v198, v186, v2
	v_mul_f32_e32 v199, v187, v6
	v_lshl_add_u64 v[204:205], v[200:201], 0, v[202:203]
	v_cvt_pk_bf16_f32 v198, v198, v199
	v_mul_f32_e32 v199, v188, v10
	v_mul_f32_e32 v200, v189, v14
	v_cvt_pk_bf16_f32 v199, v199, v200
	v_mul_f32_e32 v200, v182, v18
	v_mul_f32_e32 v201, v183, v22
	v_cvt_pk_bf16_f32 v200, v200, v201
	v_mul_f32_e32 v201, v184, v26
	v_mul_f32_e32 v212, v185, v30
	v_cvt_pk_bf16_f32 v201, v201, v212
	global_store_dwordx4 v[204:205], v[198:201], off nt
	v_mul_f32_e32 v212, v185, v31
	s_nop 0
	v_add_u32_e32 v198, 1, v227
	v_mad_i64_i32 v[198:199], s[14:15], s12, v198, 0
	v_lshl_add_u64 v[198:199], v[198:199], 1, s[4:5]
	v_lshl_add_u64 v[198:199], v[198:199], 0, s[6:7]
	v_lshl_add_u64 v[204:205], v[198:199], 0, v[202:203]
	v_mul_f32_e32 v198, v186, v3
	v_mul_f32_e32 v199, v187, v7
	v_cvt_pk_bf16_f32 v198, v198, v199
	v_mul_f32_e32 v199, v188, v11
	v_mul_f32_e32 v200, v189, v15
	v_cvt_pk_bf16_f32 v199, v199, v200
	v_mul_f32_e32 v200, v182, v19
	v_mul_f32_e32 v201, v183, v23
	v_cvt_pk_bf16_f32 v200, v200, v201
	v_mul_f32_e32 v201, v184, v27
	v_cvt_pk_bf16_f32 v201, v201, v212
	global_store_dwordx4 v[204:205], v[198:201], off nt
	v_mul_f32_e32 v212, v185, v32
	s_nop 0
	v_add_u32_e32 v198, 2, v227
	v_mad_i64_i32 v[198:199], s[14:15], s12, v198, 0
	v_lshl_add_u64 v[198:199], v[198:199], 1, s[4:5]
	v_lshl_add_u64 v[198:199], v[198:199], 0, s[6:7]
	v_lshl_add_u64 v[204:205], v[198:199], 0, v[202:203]
	v_mul_f32_e32 v198, v186, v4
	v_mul_f32_e32 v199, v187, v8
	v_cvt_pk_bf16_f32 v198, v198, v199
	v_mul_f32_e32 v199, v188, v12
	v_mul_f32_e32 v200, v189, v16
	v_cvt_pk_bf16_f32 v199, v199, v200
	v_mul_f32_e32 v200, v182, v20
	v_mul_f32_e32 v201, v183, v24
	v_cvt_pk_bf16_f32 v200, v200, v201
	v_mul_f32_e32 v201, v184, v28
	v_add_u32_e32 v227, 3, v227
	v_cvt_pk_bf16_f32 v201, v201, v212
	global_store_dwordx4 v[204:205], v[198:201], off nt
	s_nop 1
	v_mad_i64_i32 v[198:199], s[12:13], s12, v227, 0
	v_lshl_add_u64 v[198:199], v[198:199], 1, s[4:5]
	v_lshl_add_u64 v[198:199], v[198:199], 0, s[6:7]
	v_lshl_add_u64 v[202:203], v[198:199], 0, v[202:203]
	v_mul_f32_e32 v227, v186, v5
	v_mul_f32_e32 v198, v187, v9
	v_cvt_pk_bf16_f32 v198, v227, v198
	v_mul_f32_e32 v227, v188, v13
	v_mul_f32_e32 v199, v189, v17
	v_cvt_pk_bf16_f32 v199, v227, v199
	v_mul_f32_e32 v227, v182, v21
	v_mul_f32_e32 v200, v183, v25
	v_mul_f32_e32 v201, v185, v33
	v_cvt_pk_bf16_f32 v200, v227, v200
	v_mul_f32_e32 v227, v184, v29
	v_cvt_pk_bf16_f32 v201, v227, v201
	global_store_dwordx4 v[202:203], v[198:201], off nt
.Lca_done:
	s_add_i32 s36, s36, s92
	s_mov_b32 s84, 1
.Lca_skip:
	s_waitcnt lgkmcnt(5)
	v_mfma_f32_32x32x16_bf16 v[34:49], v[242:245], v[190:193], v[34:49]
	s_waitcnt lgkmcnt(4)
	v_mfma_f32_32x32x16_bf16 v[34:49], v[106:109], v[194:197], v[34:49]
	ds_read_b128 v[242:245], v248 offset:4096
	ds_read_b128 v[106:109], v249 offset:4096
	s_waitcnt lgkmcnt(2)
	v_mfma_f32_32x32x16_bf16 v[82:97], v[234:237], v[98:101], v[82:97]
	v_mfma_f32_32x32x16_bf16 v[82:97], v[238:241], v[102:105], v[82:97]
	ds_read_b128 v[234:237], v248 offset:8192
	ds_read_b128 v[238:241], v249 offset:8192
	s_waitcnt lgkmcnt(3)
	v_mfma_f32_32x32x16_bf16 v[66:81], v[242:245], v[98:101], v[66:81]
	s_waitcnt lgkmcnt(2)
	v_mfma_f32_32x32x16_bf16 v[66:81], v[106:109], v[102:105], v[66:81]
	ds_read_b128 v[242:245], v248 offset:12288
	ds_read_b128 v[106:109], v249 offset:12288
	s_waitcnt lgkmcnt(3)
	v_mfma_f32_32x32x16_bf16 v[50:65], v[234:237], v[98:101], v[50:65]
	s_waitcnt lgkmcnt(2)
	v_mfma_f32_32x32x16_bf16 v[50:65], v[238:241], v[102:105], v[50:65]
	s_waitcnt lgkmcnt(1)
	v_mfma_f32_32x32x16_bf16 v[34:49], v[242:245], v[98:101], v[34:49]
	s_waitcnt lgkmcnt(0)
	v_mfma_f32_32x32x16_bf16 v[34:49], v[106:109], v[102:105], v[34:49]
	s_add_i32 s12, s30, 0x80
	s_cmp_eq_u32 s12, s11
	s_cbranch_scc1 .Lrk_w0
	s_cmp_lg_u32 s84, 0
	s_cbranch_scc1 .Lrk_a8
	s_waitcnt vmcnt(4)
	s_branch .Lrk_wd
.Lrk_a8:
	s_waitcnt vmcnt(8)
	s_branch .LBB0_357
.Lrk_w0:
	s_cmp_lg_u32 s84, 0
	s_cbranch_scc1 .Lrk_a4
	s_waitcnt vmcnt(0)
	s_branch .Lrk_wd
.Lrk_a4:
	s_waitcnt vmcnt(4)
	s_branch .LBB0_357
